# EpiRes epilogue: LayerNorm stat loads issued together, selected by v_cndmask after the next existing vmcnt(0) (removes 8 serialized load+wait round trips per tile)
# speedup vs baseline: 1.0168x; 1.0029x over previous
; __device__ __forceinline__ unsigned cvt_pk_bf16(float lo, float hi) { unsigned r; asm volatile("v_cvt_pk_bf16_f32 %0, %1, %2" : "=v"(r) : "v"(lo), "v"(hi)); return r; }
; __device__ __forceinline__ float bflo(unsigned w) { return __uint_as_float(w << 16); }
; __device__ __forceinline__ float bfhi(unsigned w) { return __uint_as_float(w & 0xffff0000u); }
;     __device__ __forceinline__ void operator()(const f32x4 (&acc)[2][2][4][2], const Unit& u, int wr, int wc, int fr, int fq) const {
;     ...
;                 for (int m = 0; m < 4; ++m) st[m] = ln ? *(const f32x2*)(stats + 2 * (row0 + (grp ? HALF : 0) + m * 16)) : (f32x2){0.f, 1.f};
;     ...
;             for (int j = GB[grp]; j < GB[grp + 1]; ++j) {
;                 const int k = j >> 2, m = j & 3, ai = k >> 1, bj = k & 1, col = col0 + bj * HALF, kk = k - (GB[grp] >> 2);
;                 const u32x4 r = xv[j - GB[grp]];
;                 f32x4 x0 = {bflo(r.x), bfhi(r.x), bflo(r.y), bfhi(r.y)}, x1 = {bflo(r.z), bfhi(r.z), bflo(r.w), bfhi(r.w)};
;                 x0 = (x0 - st[m].x) * st[m].y * cl[kk][0] + cb[kk][0]; x1 = (x1 - st[m].x) * st[m].y * cl[kk][1] + cb[kk][1];
;                 const f32x4 o0 = x0 * ALPHA + cg[kk][0] * acc[ai][bj][m][0], o1 = x1 * ALPHA + cg[kk][1] * acc[ai][bj][m][1];
;                 u32x4 w; w.x = cvt_pk_bf16(o0[0], o0[1]); w.y = cvt_pk_bf16(o0[2], o0[3]); w.z = cvt_pk_bf16(o1[0], o1[1]); w.w = cvt_pk_bf16(o1[2], o1[3]);
;                 *(u32x4*)(z + (size_t)(row0 + ai * HALF + m * 16) * DM + col) = w;
;             }
.LBB0_175:
	s_mov_b64 s[4:5], 0x80000
	v_lshl_add_u64 v[168:169], v[150:151], 0, s[4:5]
	s_waitcnt vmcnt(0)
	v_cndmask_b32_e64 v142, v142, v145, s[12:13]
	v_cndmask_b32_e64 v136, v136, v139, s[12:13]
	v_cndmask_b32_e64 v132, v132, v135, s[12:13]
	v_cndmask_b32_e64 v128, v128, v131, s[12:13]
	v_pk_add_f32 v[150:151], v[114:115], 1.0 op_sel_hi:[1,0]
	v_pk_add_f32 v[162:163], v[112:113], 1.0 op_sel_hi:[1,0]
	v_pk_add_f32 v[164:165], v[106:107], 1.0 op_sel_hi:[1,0]
	v_pk_add_f32 v[166:167], v[104:105], 1.0 op_sel_hi:[1,0]
	v_pk_add_f32 v[170:171], v[102:103], 1.0 op_sel_hi:[1,0]
	v_pk_add_f32 v[172:173], v[100:101], 1.0 op_sel_hi:[1,0]
	v_pk_add_f32 v[174:175], v[82:83], 1.0 op_sel_hi:[1,0]
	v_pk_add_f32 v[176:177], v[80:81], 1.0 op_sel_hi:[1,0]
	global_load_dwordx4 v[112:115], v[168:169], off offset:256
	global_load_dwordx4 v[104:107], v[148:149], off offset:256
	global_load_dwordx4 v[100:103], v[146:147], off offset:256
	global_load_dwordx4 v[80:83], v[140:141], off offset:256
	v_lshlrev_b32_e32 v129, 16, v124
	v_and_b32_e32 v131, 0xffff0000, v124
	v_lshlrev_b32_e32 v124, 16, v125
	v_and_b32_e32 v125, 0xffff0000, v125
	v_lshlrev_b32_e32 v133, 16, v126
	v_and_b32_e32 v135, 0xffff0000, v126
	v_lshlrev_b32_e32 v137, 16, v127
	v_and_b32_e32 v139, 0xffff0000, v127
	v_sub_f32_e32 v125, v125, v144
	v_sub_f32_e32 v124, v124, v144
	v_sub_f32_e32 v127, v131, v144
	v_sub_f32_e32 v126, v129, v144
	v_pk_mul_f32 v[126:127], v[142:143], v[126:127] op_sel_hi:[0,1]
	v_pk_mul_f32 v[124:125], v[142:143], v[124:125] op_sel_hi:[0,1]
	v_sub_f32_e32 v179, v139, v144
	v_sub_f32_e32 v178, v137, v144
	v_sub_f32_e32 v181, v135, v144
	v_sub_f32_e32 v180, v133, v144
	v_pk_fma_f32 v[124:125], v[94:95], v[124:125], v[98:99]
	v_pk_fma_f32 v[126:127], v[92:93], v[126:127], v[96:97]
	v_pk_mul_f32 v[180:181], v[142:143], v[180:181] op_sel_hi:[0,1]
	v_pk_mul_f32 v[178:179], v[142:143], v[178:179] op_sel_hi:[0,1]
	v_pk_fma_f32 v[178:179], v[86:87], v[178:179], v[90:91]
	v_pk_fma_f32 v[180:181], v[84:85], v[180:181], v[88:89]
	v_pk_mul_f32 v[126:127], v[126:127], s[22:23] op_sel_hi:[1,0]
	v_pk_mul_f32 v[124:125], v[124:125], s[22:23] op_sel_hi:[1,0]
	v_pk_fma_f32 v[60:61], v[60:61], v[176:177], v[126:127]
	v_pk_fma_f32 v[62:63], v[62:63], v[174:175], v[124:125]
	v_pk_mul_f32 v[124:125], v[180:181], s[22:23] op_sel_hi:[1,0]
	v_pk_mul_f32 v[126:127], v[178:179], s[22:23] op_sel_hi:[1,0]
	s_and_b64 vcc, exec, s[0:1]
	v_pk_fma_f32 v[126:127], v[58:59], v[170:171], v[126:127]
	v_pk_fma_f32 v[58:59], v[56:57], v[172:173], v[124:125]
	v_cvt_pk_bf16_f32 v56, v60, v61
	v_cvt_pk_bf16_f32 v57, v62, v63
	v_lshlrev_b32_e32 v62, 16, v122
	v_cvt_pk_bf16_f32 v58, v58, v59
	v_cvt_pk_bf16_f32 v59, v126, v127
	global_store_dwordx4 v[168:169], v[56:59], off
	v_and_b32_e32 v63, 0xffff0000, v122
	v_lshlrev_b32_e32 v60, 16, v123
	v_lshlrev_b32_e32 v58, 16, v120
	v_and_b32_e32 v59, 0xffff0000, v120
	v_lshlrev_b32_e32 v56, 16, v121
	v_and_b32_e32 v57, 0xffff0000, v121
	v_and_b32_e32 v61, 0xffff0000, v123
	v_sub_f32_e32 v57, v57, v138
	v_sub_f32_e32 v56, v56, v138
	v_sub_f32_e32 v59, v59, v138
	v_sub_f32_e32 v58, v58, v138
	v_pk_mul_f32 v[58:59], v[136:137], v[58:59] op_sel_hi:[0,1]
	v_pk_mul_f32 v[56:57], v[136:137], v[56:57] op_sel_hi:[0,1]
	v_sub_f32_e32 v61, v61, v138
	v_sub_f32_e32 v60, v60, v138
	v_sub_f32_e32 v63, v63, v138
	v_sub_f32_e32 v62, v62, v138
	v_pk_fma_f32 v[56:57], v[94:95], v[56:57], v[98:99]
	v_pk_fma_f32 v[58:59], v[92:93], v[58:59], v[96:97]
	v_pk_mul_f32 v[62:63], v[136:137], v[62:63] op_sel_hi:[0,1]
	v_pk_mul_f32 v[60:61], v[136:137], v[60:61] op_sel_hi:[0,1]
	v_pk_fma_f32 v[60:61], v[86:87], v[60:61], v[90:91]
	v_pk_fma_f32 v[62:63], v[84:85], v[62:63], v[88:89]
	v_pk_mul_f32 v[58:59], v[58:59], s[22:23] op_sel_hi:[1,0]
	v_pk_mul_f32 v[56:57], v[56:57], s[22:23] op_sel_hi:[1,0]
	v_pk_fma_f32 v[52:53], v[52:53], v[176:177], v[58:59]
	v_pk_fma_f32 v[54:55], v[54:55], v[174:175], v[56:57]
	v_pk_mul_f32 v[56:57], v[62:63], s[22:23] op_sel_hi:[1,0]
	v_pk_mul_f32 v[58:59], v[60:61], s[22:23] op_sel_hi:[1,0]
	s_mov_b32 s48, s46
	v_pk_fma_f32 v[58:59], v[50:51], v[170:171], v[58:59]
	v_pk_fma_f32 v[50:51], v[48:49], v[172:173], v[56:57]
	v_cvt_pk_bf16_f32 v48, v52, v53
	v_cvt_pk_bf16_f32 v49, v54, v55
	v_lshlrev_b32_e32 v54, 16, v118
	v_cvt_pk_bf16_f32 v50, v50, v51
	v_cvt_pk_bf16_f32 v51, v58, v59
	global_store_dwordx4 v[148:149], v[48:51], off
	v_and_b32_e32 v55, 0xffff0000, v118
	v_lshlrev_b32_e32 v52, 16, v119
	v_lshlrev_b32_e32 v50, 16, v116
	v_and_b32_e32 v51, 0xffff0000, v116
	v_lshlrev_b32_e32 v48, 16, v117
	v_and_b32_e32 v49, 0xffff0000, v117
	v_and_b32_e32 v53, 0xffff0000, v119
	v_sub_f32_e32 v49, v49, v134
	v_sub_f32_e32 v48, v48, v134
	v_sub_f32_e32 v51, v51, v134
	v_sub_f32_e32 v50, v50, v134
	v_pk_mul_f32 v[50:51], v[132:133], v[50:51] op_sel_hi:[0,1]
	v_pk_mul_f32 v[48:49], v[132:133], v[48:49] op_sel_hi:[0,1]
	v_sub_f32_e32 v53, v53, v134
	v_sub_f32_e32 v52, v52, v134
	v_sub_f32_e32 v55, v55, v134
	v_sub_f32_e32 v54, v54, v134
	v_pk_fma_f32 v[48:49], v[94:95], v[48:49], v[98:99]
	v_pk_fma_f32 v[50:51], v[92:93], v[50:51], v[96:97]
	v_pk_mul_f32 v[54:55], v[132:133], v[54:55] op_sel_hi:[0,1]
	v_pk_mul_f32 v[52:53], v[132:133], v[52:53] op_sel_hi:[0,1]
	v_pk_fma_f32 v[52:53], v[86:87], v[52:53], v[90:91]
	v_pk_fma_f32 v[54:55], v[84:85], v[54:55], v[88:89]
	v_pk_mul_f32 v[50:51], v[50:51], s[22:23] op_sel_hi:[1,0]
	v_pk_mul_f32 v[48:49], v[48:49], s[22:23] op_sel_hi:[1,0]
	v_pk_fma_f32 v[44:45], v[44:45], v[176:177], v[50:51]
	v_pk_fma_f32 v[46:47], v[46:47], v[174:175], v[48:49]
	v_pk_mul_f32 v[48:49], v[54:55], s[22:23] op_sel_hi:[1,0]
	v_pk_mul_f32 v[50:51], v[52:53], s[22:23] op_sel_hi:[1,0]
; __device__ __forceinline__ unsigned cvt_pk_bf16(float lo, float hi) { unsigned r; asm volatile("v_cvt_pk_bf16_f32 %0, %1, %2" : "=v"(r) : "v"(lo), "v"(hi)); return r; }
; __device__ __forceinline__ float bflo(unsigned w) { return __uint_as_float(w << 16); }
; __device__ __forceinline__ float bfhi(unsigned w) { return __uint_as_float(w & 0xffff0000u); }
;     __device__ __forceinline__ void operator()(const f32x4 (&acc)[2][2][4][2], const Unit& u, int wr, int wc, int fr, int fq) const {
;     ...
;             for (int j = GB[grp]; j < GB[grp + 1]; ++j) {
;                 const int k = j >> 2, m = j & 3, ai = k >> 1, bj = k & 1, col = col0 + bj * HALF, kk = k - (GB[grp] >> 2);
;                 const u32x4 r = xv[j - GB[grp]];
;                 f32x4 x0 = {bflo(r.x), bfhi(r.x), bflo(r.y), bfhi(r.y)}, x1 = {bflo(r.z), bfhi(r.z), bflo(r.w), bfhi(r.w)};
;                 x0 = (x0 - st[m].x) * st[m].y * cl[kk][0] + cb[kk][0]; x1 = (x1 - st[m].x) * st[m].y * cl[kk][1] + cb[kk][1];
;                 const f32x4 o0 = x0 * ALPHA + cg[kk][0] * acc[ai][bj][m][0], o1 = x1 * ALPHA + cg[kk][1] * acc[ai][bj][m][1];
;                 u32x4 w; w.x = cvt_pk_bf16(o0[0], o0[1]); w.y = cvt_pk_bf16(o0[2], o0[3]); w.z = cvt_pk_bf16(o1[0], o1[1]); w.w = cvt_pk_bf16(o1[2], o1[3]);
;                 *(u32x4*)(z + (size_t)(row0 + ai * HALF + m * 16) * DM + col) = w;
;             }
	s_mov_b32 s49, s47
	v_pk_fma_f32 v[50:51], v[42:43], v[170:171], v[50:51]
	v_pk_fma_f32 v[42:43], v[40:41], v[172:173], v[48:49]
	v_cvt_pk_bf16_f32 v40, v44, v45
	v_cvt_pk_bf16_f32 v41, v46, v47
	v_lshlrev_b32_e32 v46, 16, v110
	v_cvt_pk_bf16_f32 v42, v42, v43
	v_cvt_pk_bf16_f32 v43, v50, v51
	global_store_dwordx4 v[146:147], v[40:43], off
	v_and_b32_e32 v47, 0xffff0000, v110
	v_lshlrev_b32_e32 v44, 16, v111
	v_lshlrev_b32_e32 v42, 16, v108
	v_and_b32_e32 v43, 0xffff0000, v108
	v_lshlrev_b32_e32 v40, 16, v109
	v_and_b32_e32 v41, 0xffff0000, v109
	v_and_b32_e32 v45, 0xffff0000, v111
	v_sub_f32_e32 v41, v41, v130
	v_sub_f32_e32 v40, v40, v130
	v_sub_f32_e32 v43, v43, v130
	v_sub_f32_e32 v42, v42, v130
	v_pk_mul_f32 v[42:43], v[128:129], v[42:43] op_sel_hi:[0,1]
	v_pk_mul_f32 v[40:41], v[128:129], v[40:41] op_sel_hi:[0,1]
	v_sub_f32_e32 v45, v45, v130
	v_sub_f32_e32 v44, v44, v130
	v_sub_f32_e32 v47, v47, v130
	v_sub_f32_e32 v46, v46, v130
	v_pk_fma_f32 v[40:41], v[94:95], v[40:41], v[98:99]
	v_pk_fma_f32 v[42:43], v[92:93], v[42:43], v[96:97]
	v_pk_mul_f32 v[46:47], v[128:129], v[46:47] op_sel_hi:[0,1]
	v_pk_mul_f32 v[44:45], v[128:129], v[44:45] op_sel_hi:[0,1]
	v_pk_fma_f32 v[44:45], v[86:87], v[44:45], v[90:91]
	v_pk_fma_f32 v[46:47], v[84:85], v[46:47], v[88:89]
	v_pk_mul_f32 v[42:43], v[42:43], s[22:23] op_sel_hi:[1,0]
	v_pk_mul_f32 v[40:41], v[40:41], s[22:23] op_sel_hi:[1,0]
	v_pk_fma_f32 v[36:37], v[36:37], v[176:177], v[42:43]
	v_pk_fma_f32 v[38:39], v[38:39], v[174:175], v[40:41]
	v_pk_mul_f32 v[40:41], v[46:47], s[22:23] op_sel_hi:[1,0]
	v_pk_mul_f32 v[42:43], v[44:45], s[22:23] op_sel_hi:[1,0]
	s_mov_b64 s[24:25], s[6:7]
	v_pk_fma_f32 v[42:43], v[34:35], v[170:171], v[42:43]
	v_pk_fma_f32 v[34:35], v[32:33], v[172:173], v[40:41]
	v_cvt_pk_bf16_f32 v32, v36, v37
	v_cvt_pk_bf16_f32 v33, v38, v39
	s_waitcnt vmcnt(0)
; __device__ __forceinline__ unsigned cvt_pk_bf16(float lo, float hi) { unsigned r; asm volatile("v_cvt_pk_bf16_f32 %0, %1, %2" : "=v"(r) : "v"(lo), "v"(hi)); return r; }
; __device__ __forceinline__ float bflo(unsigned w) { return __uint_as_float(w << 16); }
; __device__ __forceinline__ float bfhi(unsigned w) { return __uint_as_float(w & 0xffff0000u); }
;     __device__ __forceinline__ void operator()(const f32x4 (&acc)[2][2][4][2], const Unit& u, int wr, int wc, int fr, int fq) const {
;     ...
;             for (int j = GB[grp]; j < GB[grp + 1]; ++j) {
;                 const int k = j >> 2, m = j & 3, ai = k >> 1, bj = k & 1, col = col0 + bj * HALF, kk = k - (GB[grp] >> 2);
;                 const u32x4 r = xv[j - GB[grp]];
;                 f32x4 x0 = {bflo(r.x), bfhi(r.x), bflo(r.y), bfhi(r.y)}, x1 = {bflo(r.z), bfhi(r.z), bflo(r.w), bfhi(r.w)};
;                 x0 = (x0 - st[m].x) * st[m].y * cl[kk][0] + cb[kk][0]; x1 = (x1 - st[m].x) * st[m].y * cl[kk][1] + cb[kk][1];
;                 const f32x4 o0 = x0 * ALPHA + cg[kk][0] * acc[ai][bj][m][0], o1 = x1 * ALPHA + cg[kk][1] * acc[ai][bj][m][1];
;                 u32x4 w; w.x = cvt_pk_bf16(o0[0], o0[1]); w.y = cvt_pk_bf16(o0[2], o0[3]); w.z = cvt_pk_bf16(o1[0], o1[1]); w.w = cvt_pk_bf16(o1[2], o1[3]);
;                 *(u32x4*)(z + (size_t)(row0 + ai * HALF + m * 16) * DM + col) = w;
;             }
	v_lshlrev_b32_e32 v38, 16, v114
	v_cvt_pk_bf16_f32 v34, v34, v35
	v_cvt_pk_bf16_f32 v35, v42, v43
	global_store_dwordx4 v[140:141], v[32:35], off
	v_and_b32_e32 v39, 0xffff0000, v114
	v_lshlrev_b32_e32 v36, 16, v115
	v_lshlrev_b32_e32 v34, 16, v112
	v_and_b32_e32 v35, 0xffff0000, v112
	v_lshlrev_b32_e32 v32, 16, v113
	v_and_b32_e32 v33, 0xffff0000, v113
	v_and_b32_e32 v37, 0xffff0000, v115
	v_sub_f32_e32 v33, v33, v144
	v_sub_f32_e32 v32, v32, v144
	v_sub_f32_e32 v35, v35, v144
	v_sub_f32_e32 v34, v34, v144
	v_pk_mul_f32 v[34:35], v[142:143], v[34:35] op_sel_hi:[0,1]
	v_pk_mul_f32 v[32:33], v[142:143], v[32:33] op_sel_hi:[0,1]
	v_sub_f32_e32 v37, v37, v144
	v_sub_f32_e32 v36, v36, v144
	v_sub_f32_e32 v39, v39, v144
	v_sub_f32_e32 v38, v38, v144
	v_pk_fma_f32 v[32:33], v[74:75], v[32:33], v[78:79]
	v_pk_fma_f32 v[34:35], v[72:73], v[34:35], v[76:77]
	v_pk_mul_f32 v[38:39], v[142:143], v[38:39] op_sel_hi:[0,1]
	v_pk_mul_f32 v[36:37], v[142:143], v[36:37] op_sel_hi:[0,1]
	v_pk_fma_f32 v[36:37], v[66:67], v[36:37], v[70:71]
	v_pk_fma_f32 v[38:39], v[64:65], v[38:39], v[68:69]
	v_pk_mul_f32 v[34:35], v[34:35], s[22:23] op_sel_hi:[1,0]
	v_pk_mul_f32 v[32:33], v[32:33], s[22:23] op_sel_hi:[1,0]
	v_pk_fma_f32 v[28:29], v[28:29], v[166:167], v[34:35]
	v_pk_fma_f32 v[30:31], v[30:31], v[164:165], v[32:33]
	v_pk_mul_f32 v[32:33], v[38:39], s[22:23] op_sel_hi:[1,0]
	v_pk_mul_f32 v[34:35], v[36:37], s[22:23] op_sel_hi:[1,0]
	s_nop 0
	v_pk_fma_f32 v[34:35], v[26:27], v[150:151], v[34:35]
	v_pk_fma_f32 v[26:27], v[24:25], v[162:163], v[32:33]
	v_cvt_pk_bf16_f32 v24, v28, v29
	v_cvt_pk_bf16_f32 v25, v30, v31
	v_lshlrev_b32_e32 v30, 16, v106
	v_cvt_pk_bf16_f32 v26, v26, v27
	v_cvt_pk_bf16_f32 v27, v34, v35
	global_store_dwordx4 v[168:169], v[24:27], off offset:256
	v_and_b32_e32 v31, 0xffff0000, v106
	v_lshlrev_b32_e32 v28, 16, v107
	v_lshlrev_b32_e32 v26, 16, v104
	v_and_b32_e32 v27, 0xffff0000, v104
	v_lshlrev_b32_e32 v24, 16, v105
	v_and_b32_e32 v25, 0xffff0000, v105
	v_and_b32_e32 v29, 0xffff0000, v107
	v_sub_f32_e32 v25, v25, v138
	v_sub_f32_e32 v24, v24, v138
	v_sub_f32_e32 v27, v27, v138
	v_sub_f32_e32 v26, v26, v138
	v_pk_mul_f32 v[26:27], v[136:137], v[26:27] op_sel_hi:[0,1]
	v_pk_mul_f32 v[24:25], v[136:137], v[24:25] op_sel_hi:[0,1]
	v_sub_f32_e32 v29, v29, v138
	v_sub_f32_e32 v28, v28, v138
	v_sub_f32_e32 v31, v31, v138
	v_sub_f32_e32 v30, v30, v138
	v_pk_fma_f32 v[24:25], v[74:75], v[24:25], v[78:79]
	v_pk_fma_f32 v[26:27], v[72:73], v[26:27], v[76:77]
	v_pk_mul_f32 v[30:31], v[136:137], v[30:31] op_sel_hi:[0,1]
	v_pk_mul_f32 v[28:29], v[136:137], v[28:29] op_sel_hi:[0,1]
	v_pk_fma_f32 v[28:29], v[66:67], v[28:29], v[70:71]
	v_pk_fma_f32 v[30:31], v[64:65], v[30:31], v[68:69]
	v_pk_mul_f32 v[26:27], v[26:27], s[22:23] op_sel_hi:[1,0]
	v_pk_mul_f32 v[24:25], v[24:25], s[22:23] op_sel_hi:[1,0]
	v_pk_fma_f32 v[20:21], v[20:21], v[166:167], v[26:27]
	v_pk_fma_f32 v[22:23], v[22:23], v[164:165], v[24:25]
	v_pk_mul_f32 v[24:25], v[30:31], s[22:23] op_sel_hi:[1,0]
	v_pk_mul_f32 v[26:27], v[28:29], s[22:23] op_sel_hi:[1,0]
	s_nop 0
	v_pk_fma_f32 v[26:27], v[18:19], v[150:151], v[26:27]
	v_pk_fma_f32 v[18:19], v[16:17], v[162:163], v[24:25]
	v_cvt_pk_bf16_f32 v16, v20, v21
	v_cvt_pk_bf16_f32 v17, v22, v23
	v_lshlrev_b32_e32 v22, 16, v102
	v_cvt_pk_bf16_f32 v18, v18, v19
	v_cvt_pk_bf16_f32 v19, v26, v27
	global_store_dwordx4 v[148:149], v[16:19], off offset:256
	v_and_b32_e32 v23, 0xffff0000, v102
	v_lshlrev_b32_e32 v20, 16, v103
	v_lshlrev_b32_e32 v18, 16, v100
	v_and_b32_e32 v19, 0xffff0000, v100
	v_lshlrev_b32_e32 v16, 16, v101
	v_and_b32_e32 v17, 0xffff0000, v101
	v_and_b32_e32 v21, 0xffff0000, v103
	v_sub_f32_e32 v17, v17, v134
	v_sub_f32_e32 v16, v16, v134
	v_sub_f32_e32 v19, v19, v134
	v_sub_f32_e32 v18, v18, v134
	v_pk_mul_f32 v[18:19], v[132:133], v[18:19] op_sel_hi:[0,1]
	v_pk_mul_f32 v[16:17], v[132:133], v[16:17] op_sel_hi:[0,1]
	v_sub_f32_e32 v21, v21, v134
	v_sub_f32_e32 v20, v20, v134
	v_sub_f32_e32 v23, v23, v134
	v_sub_f32_e32 v22, v22, v134
	v_pk_fma_f32 v[16:17], v[74:75], v[16:17], v[78:79]
	v_pk_fma_f32 v[18:19], v[72:73], v[18:19], v[76:77]
	v_pk_mul_f32 v[22:23], v[132:133], v[22:23] op_sel_hi:[0,1]
	v_pk_mul_f32 v[20:21], v[132:133], v[20:21] op_sel_hi:[0,1]
	v_pk_fma_f32 v[20:21], v[66:67], v[20:21], v[70:71]
	v_pk_fma_f32 v[22:23], v[64:65], v[22:23], v[68:69]
	v_pk_mul_f32 v[18:19], v[18:19], s[22:23] op_sel_hi:[1,0]
	v_pk_mul_f32 v[16:17], v[16:17], s[22:23] op_sel_hi:[1,0]
	v_pk_fma_f32 v[12:13], v[12:13], v[166:167], v[18:19]
	v_pk_fma_f32 v[14:15], v[14:15], v[164:165], v[16:17]
	v_pk_mul_f32 v[16:17], v[22:23], s[22:23] op_sel_hi:[1,0]
	v_pk_mul_f32 v[18:19], v[20:21], s[22:23] op_sel_hi:[1,0]
	s_nop 0
	v_pk_fma_f32 v[18:19], v[10:11], v[150:151], v[18:19]
	v_pk_fma_f32 v[10:11], v[8:9], v[162:163], v[16:17]
	v_cvt_pk_bf16_f32 v8, v12, v13
	v_cvt_pk_bf16_f32 v9, v14, v15
	v_lshlrev_b32_e32 v14, 16, v82
	v_cvt_pk_bf16_f32 v10, v10, v11
	v_cvt_pk_bf16_f32 v11, v18, v19
	global_store_dwordx4 v[146:147], v[8:11], off offset:256
	v_and_b32_e32 v15, 0xffff0000, v82
	v_lshlrev_b32_e32 v12, 16, v83
	v_lshlrev_b32_e32 v10, 16, v80
	v_and_b32_e32 v11, 0xffff0000, v80
	v_lshlrev_b32_e32 v8, 16, v81
	v_and_b32_e32 v9, 0xffff0000, v81
	v_and_b32_e32 v13, 0xffff0000, v83
	v_sub_f32_e32 v9, v9, v130
	v_sub_f32_e32 v8, v8, v130
	v_sub_f32_e32 v11, v11, v130
	v_sub_f32_e32 v10, v10, v130
	v_pk_mul_f32 v[10:11], v[128:129], v[10:11] op_sel_hi:[0,1]
	v_pk_mul_f32 v[8:9], v[128:129], v[8:9] op_sel_hi:[0,1]
	v_sub_f32_e32 v13, v13, v130
	v_sub_f32_e32 v12, v12, v130
	v_sub_f32_e32 v15, v15, v130
	v_sub_f32_e32 v14, v14, v130
	v_pk_fma_f32 v[8:9], v[74:75], v[8:9], v[78:79]
	v_pk_fma_f32 v[10:11], v[72:73], v[10:11], v[76:77]
	v_pk_mul_f32 v[14:15], v[128:129], v[14:15] op_sel_hi:[0,1]
	v_pk_mul_f32 v[12:13], v[128:129], v[12:13] op_sel_hi:[0,1]
	v_pk_fma_f32 v[12:13], v[66:67], v[12:13], v[70:71]
	v_pk_fma_f32 v[14:15], v[64:65], v[14:15], v[68:69]
	v_pk_mul_f32 v[10:11], v[10:11], s[22:23] op_sel_hi:[1,0]
	v_pk_mul_f32 v[8:9], v[8:9], s[22:23] op_sel_hi:[1,0]
	v_pk_fma_f32 v[4:5], v[4:5], v[166:167], v[10:11]
	v_pk_fma_f32 v[6:7], v[6:7], v[164:165], v[8:9]
	v_pk_mul_f32 v[8:9], v[14:15], s[22:23] op_sel_hi:[1,0]
	v_pk_mul_f32 v[10:11], v[12:13], s[22:23] op_sel_hi:[1,0]
	s_mov_b64 s[22:23], s[20:21]
	v_pk_fma_f32 v[10:11], v[2:3], v[150:151], v[10:11]
	v_pk_fma_f32 v[2:3], v[0:1], v[162:163], v[8:9]
	v_cvt_pk_bf16_f32 v0, v4, v5
	v_cvt_pk_bf16_f32 v1, v6, v7
	s_nop 0
	v_cvt_pk_bf16_f32 v2, v2, v3
	v_cvt_pk_bf16_f32 v3, v10, v11
	global_store_dwordx4 v[140:141], v[0:3], off offset:256
	s_cbranch_vccnz .LBB0_220

;     __device__ __forceinline__ void operator()(const f32x4 (&acc)[2][2][4][2], const Unit& u, int wr, int wc, int fr, int fq) const {
;     ...
;             if (grp == 0 || grp == 2) {
; #pragma unroll
;                 for (int m = 0; m < 4; ++m) st[m] = ln ? *(const f32x2*)(stats + 2 * (row0 + (grp ? HALF : 0) + m * 16)) : (f32x2){0.f, 1.f};
;             }
; #pragma unroll
;             for (int j = GB[grp]; j < GB[grp + 1]; ++j) {
;                 const int k = j >> 2, m = j & 3, ai = k >> 1, col = col0 + (k & 1) * HALF, kk = k - (GB[grp] >> 2);
;                 if (m == 0) {
; #pragma unroll
;                     for (int n = 0; n < 2; ++n) { cg[kk][n] = *(const f32x4*)(gb + col + 4 * n) + 1.0f; cl[kk][n] = (f32x4){1.f, 1.f, 1.f, 1.f}; cb[kk][n] = (f32x4){0.f, 0.f, 0.f, 0.f};
;                         if (ln) { cl[kk][n] = *(const f32x4*)(lng + col + 4 * n); cb[kk][n] = *(const f32x4*)(lnb + col + 4 * n); } }
;                 }
;                 xv[j - GB[grp]] = *(const u32x4*)(z + (size_t)(row0 + ai * HALF + m * 16) * DM + col);
.Lpeel_done_187:
	s_lshl_b32 s22, s49, 8
	s_add_i32 s22, s22, s37
	v_or_b32_e32 v162, s22, v206
	v_lshlrev_b32_e32 v170, 1, v162
	v_cndmask_b32_e64 v128, 0, 1, s[12:13]
	v_mov_b32_e32 v182, 1.0
	v_mov_b32_e32 v184, 0
	v_cmp_ne_u32_e64 s[4:5], 1, v128
	s_andn2_b64 vcc, exec, s[12:13]
	v_ashrrev_i32_e32 v171, 31, v170
	v_mov_b32_e32 v192, 0
	v_mov_b32_e32 v194, 1.0
	v_mov_b32_e32 v176, 1.0
	v_mov_b32_e32 v174, 0
	v_mov_b32_e32 v178, 0
	v_mov_b32_e32 v180, 1.0
	s_mov_b32 s54, 0xd00ab22c
	s_mov_b32 s55, 0x3febb5fa
	s_cbranch_vccnz .Lres_st1_skip
	v_lshl_add_u64 v[128:129], v[170:171], 2, s[14:15]
	global_load_dwordx2 v[192:193], v[128:129], off
	global_load_dwordx2 v[184:185], v[128:129], off offset:128
	global_load_dwordx2 v[178:179], v[128:129], off offset:256
	global_load_dwordx2 v[174:175], v[128:129], off offset:384
.Lres_st1_skip:
.LBB0_196:
	s_ashr_i32 s22, s22, 12
	v_lshl_or_b32 v172, s48, 8, v208
	s_mul_hi_i32 s23, s22, 0xc000
	s_mul_i32 s22, s22, 0xc000
	s_add_u32 s22, s43, s22
	v_ashrrev_i32_e32 v173, 31, v172
	s_addc_u32 s23, s44, s23
	v_lshlrev_b64 v[128:129], 2, v[172:173]
	v_lshl_add_u64 v[168:169], s[22:23], 0, v[128:129]
	global_load_dwordx4 v[144:147], v[168:169], off
	v_lshl_add_u64 v[164:165], s[8:9], 0, v[128:129]
	v_lshl_add_u64 v[166:167], s[10:11], 0, v[128:129]
	v_mov_b32_e32 v132, 0
	v_mov_b32_e32 v128, 1.0
	s_and_b64 vcc, exec, s[4:5]
	v_mov_b32_e32 v136, 1.0
	v_mov_b32_e32 v137, 1.0
	v_mov_b32_e32 v138, 1.0
	v_mov_b32_e32 v139, 1.0
	v_mov_b32_e32 v140, 0
	v_mov_b32_e32 v141, 0
	v_mov_b32_e32 v142, 0
	v_mov_b32_e32 v143, 0
	s_cbranch_vccnz .LBB0_198
	global_load_dwordx4 v[136:139], v[164:165], off
	global_load_dwordx4 v[140:143], v[166:167], off

; __device__ __forceinline__ unsigned cvt_pk_bf16(float lo, float hi) { unsigned r; asm volatile("v_cvt_pk_bf16_f32 %0, %1, %2" : "=v"(r) : "v"(lo), "v"(hi)); return r; }
; __device__ __forceinline__ float bflo(unsigned w) { return __uint_as_float(w << 16); }
; __device__ __forceinline__ float bfhi(unsigned w) { return __uint_as_float(w & 0xffff0000u); }
;     __device__ __forceinline__ void operator()(const f32x4 (&acc)[2][2][4][2], const Unit& u, int wr, int wc, int fr, int fq) const {
;     ...
;                 xv[j - GB[grp]] = *(const u32x4*)(z + (size_t)(row0 + ai * HALF + m * 16) * DM + col);
;             }
; #pragma unroll
;             for (int j = GB[grp]; j < GB[grp + 1]; ++j) {
;                 const int k = j >> 2, m = j & 3, ai = k >> 1, bj = k & 1, col = col0 + bj * HALF, kk = k - (GB[grp] >> 2);
;                 const u32x4 r = xv[j - GB[grp]];
;                 f32x4 x0 = {bflo(r.x), bfhi(r.x), bflo(r.y), bfhi(r.y)}, x1 = {bflo(r.z), bfhi(r.z), bflo(r.w), bfhi(r.w)};
;                 x0 = (x0 - st[m].x) * st[m].y * cl[kk][0] + cb[kk][0]; x1 = (x1 - st[m].x) * st[m].y * cl[kk][1] + cb[kk][1];
;                 const f32x4 o0 = x0 * ALPHA + cg[kk][0] * acc[ai][bj][m][0], o1 = x1 * ALPHA + cg[kk][1] * acc[ai][bj][m][1];
;                 u32x4 w; w.x = cvt_pk_bf16(o0[0], o0[1]); w.y = cvt_pk_bf16(o0[2], o0[3]); w.z = cvt_pk_bf16(o1[0], o1[1]); w.w = cvt_pk_bf16(o1[2], o1[3]);
;                 *(u32x4*)(z + (size_t)(row0 + ai * HALF + m * 16) * DM + col) = w;
;             }
.LBB0_200:
	v_ashrrev_i32_e32 v163, 31, v162
	s_waitcnt vmcnt(0)
	v_cndmask_b32_e64 v194, v194, v193, s[12:13]
	v_cndmask_b32_e64 v182, v182, v185, s[12:13]
	v_cndmask_b32_e64 v180, v180, v179, s[12:13]
	v_cndmask_b32_e64 v176, v176, v175, s[12:13]
	v_pk_add_f32 v[204:205], v[144:145], 1.0 op_sel_hi:[1,0]
	v_lshlrev_b64 v[144:145], 12, v[162:163]
	v_lshl_add_u64 v[144:145], s[82:83], 0, v[144:145]
	v_lshlrev_b64 v[172:173], 1, v[172:173]
	v_lshl_add_u64 v[196:197], v[144:145], 0, v[172:173]
	global_load_dwordx4 v[210:213], v[196:197], off
	v_or_b32_e32 v144, 16, v162
	v_ashrrev_i32_e32 v145, 31, v144
	v_lshlrev_b64 v[144:145], 12, v[144:145]
	v_lshl_add_u64 v[144:145], s[82:83], 0, v[144:145]
	v_lshl_add_u64 v[190:191], v[144:145], 0, v[172:173]
	global_load_dwordx4 v[214:217], v[190:191], off
	v_or_b32_e32 v144, 32, v162
	v_ashrrev_i32_e32 v145, 31, v144
	v_lshlrev_b64 v[144:145], 12, v[144:145]
	v_lshl_add_u64 v[144:145], s[82:83], 0, v[144:145]
	v_lshl_add_u64 v[188:189], v[144:145], 0, v[172:173]
	v_pk_add_f32 v[198:199], v[150:151], 1.0 op_sel_hi:[1,0]
	v_pk_add_f32 v[200:201], v[148:149], 1.0 op_sel_hi:[1,0]
	global_load_dwordx4 v[148:151], v[188:189], off
	v_or_b32_e32 v144, 48, v162
	v_ashrrev_i32_e32 v145, 31, v144
	v_lshlrev_b64 v[144:145], 12, v[144:145]
	v_lshl_add_u64 v[144:145], s[82:83], 0, v[144:145]
	v_lshl_add_u64 v[186:187], v[144:145], 0, v[172:173]
	v_pk_add_f32 v[202:203], v[146:147], 1.0 op_sel_hi:[1,0]
	global_load_dwordx4 v[144:147], v[186:187], off
	s_and_b64 vcc, exec, s[4:5]
	s_waitcnt vmcnt(0)
	v_lshlrev_b32_e32 v175, 16, v210
	v_and_b32_e32 v177, 0xffff0000, v210
	v_lshlrev_b32_e32 v179, 16, v211
	v_and_b32_e32 v181, 0xffff0000, v211
	v_lshlrev_b32_e32 v183, 16, v212
	v_and_b32_e32 v185, 0xffff0000, v212
	v_lshlrev_b32_e32 v193, 16, v213
	v_and_b32_e32 v195, 0xffff0000, v213
	v_sub_f32_e32 v211, v181, v192
	v_sub_f32_e32 v210, v179, v192
	v_sub_f32_e32 v213, v177, v192
	v_sub_f32_e32 v212, v175, v192
	v_pk_mul_f32 v[212:213], v[194:195], v[212:213] op_sel_hi:[0,1]
	v_pk_mul_f32 v[210:211], v[194:195], v[210:211] op_sel_hi:[0,1]
	v_sub_f32_e32 v219, v195, v192
	v_sub_f32_e32 v218, v193, v192
	v_sub_f32_e32 v229, v185, v192
	v_sub_f32_e32 v228, v183, v192
	v_pk_fma_f32 v[210:211], v[138:139], v[210:211], v[142:143]
	v_pk_fma_f32 v[212:213], v[136:137], v[212:213], v[140:141]
	v_pk_mul_f32 v[228:229], v[194:195], v[228:229] op_sel_hi:[0,1]
	v_pk_mul_f32 v[218:219], v[194:195], v[218:219] op_sel_hi:[0,1]
	v_pk_fma_f32 v[218:219], v[130:131], v[218:219], v[134:135]
	v_pk_fma_f32 v[228:229], v[128:129], v[228:229], v[132:133]
	v_pk_mul_f32 v[212:213], v[212:213], s[22:23] op_sel_hi:[1,0]
	v_pk_mul_f32 v[210:211], v[210:211], s[22:23] op_sel_hi:[1,0]
	v_pk_fma_f32 v[124:125], v[124:125], v[204:205], v[212:213]
	v_pk_fma_f32 v[126:127], v[126:127], v[202:203], v[210:211]
	v_pk_mul_f32 v[210:211], v[228:229], s[22:23] op_sel_hi:[1,0]
	v_pk_mul_f32 v[212:213], v[218:219], s[22:23] op_sel_hi:[1,0]
	s_nop 0
	v_pk_fma_f32 v[212:213], v[122:123], v[198:199], v[212:213]
	v_pk_fma_f32 v[122:123], v[120:121], v[200:201], v[210:211]
	v_cvt_pk_bf16_f32 v120, v124, v125
	v_cvt_pk_bf16_f32 v121, v126, v127
	v_lshlrev_b32_e32 v126, 16, v216
	v_cvt_pk_bf16_f32 v122, v122, v123
	v_cvt_pk_bf16_f32 v123, v212, v213
	global_store_dwordx4 v[196:197], v[120:123], off
	v_and_b32_e32 v127, 0xffff0000, v216
	v_lshlrev_b32_e32 v124, 16, v217
	v_lshlrev_b32_e32 v122, 16, v214
	v_and_b32_e32 v123, 0xffff0000, v214
	v_lshlrev_b32_e32 v120, 16, v215
	v_and_b32_e32 v121, 0xffff0000, v215
	v_and_b32_e32 v125, 0xffff0000, v217
	v_sub_f32_e32 v121, v121, v184
	v_sub_f32_e32 v120, v120, v184
	v_sub_f32_e32 v123, v123, v184
	v_sub_f32_e32 v122, v122, v184
	v_pk_mul_f32 v[122:123], v[182:183], v[122:123] op_sel_hi:[0,1]
	v_pk_mul_f32 v[120:121], v[182:183], v[120:121] op_sel_hi:[0,1]
	v_sub_f32_e32 v125, v125, v184
	v_sub_f32_e32 v124, v124, v184
	v_sub_f32_e32 v127, v127, v184
	v_sub_f32_e32 v126, v126, v184
	v_pk_fma_f32 v[120:121], v[138:139], v[120:121], v[142:143]
	v_pk_fma_f32 v[122:123], v[136:137], v[122:123], v[140:141]
	v_pk_mul_f32 v[126:127], v[182:183], v[126:127] op_sel_hi:[0,1]
	v_pk_mul_f32 v[124:125], v[182:183], v[124:125] op_sel_hi:[0,1]
	v_pk_fma_f32 v[124:125], v[130:131], v[124:125], v[134:135]
	v_pk_fma_f32 v[126:127], v[128:129], v[126:127], v[132:133]
	v_pk_mul_f32 v[122:123], v[122:123], s[22:23] op_sel_hi:[1,0]
	v_pk_mul_f32 v[120:121], v[120:121], s[22:23] op_sel_hi:[1,0]
; __device__ __forceinline__ unsigned cvt_pk_bf16(float lo, float hi) { unsigned r; asm volatile("v_cvt_pk_bf16_f32 %0, %1, %2" : "=v"(r) : "v"(lo), "v"(hi)); return r; }
; __device__ __forceinline__ float bflo(unsigned w) { return __uint_as_float(w << 16); }
; __device__ __forceinline__ float bfhi(unsigned w) { return __uint_as_float(w & 0xffff0000u); }
;     __device__ __forceinline__ void operator()(const f32x4 (&acc)[2][2][4][2], const Unit& u, int wr, int wc, int fr, int fq) const {
;     ...
;             for (int j = GB[grp]; j < GB[grp + 1]; ++j) {
;                 const int k = j >> 2, m = j & 3, ai = k >> 1, col = col0 + (k & 1) * HALF, kk = k - (GB[grp] >> 2);
;                 if (m == 0) {
; #pragma unroll
;                     for (int n = 0; n < 2; ++n) { cg[kk][n] = *(const f32x4*)(gb + col + 4 * n) + 1.0f; cl[kk][n] = (f32x4){1.f, 1.f, 1.f, 1.f}; cb[kk][n] = (f32x4){0.f, 0.f, 0.f, 0.f};
;                         if (ln) { cl[kk][n] = *(const f32x4*)(lng + col + 4 * n); cb[kk][n] = *(const f32x4*)(lnb + col + 4 * n); } }
;                 }
;                 xv[j - GB[grp]] = *(const u32x4*)(z + (size_t)(row0 + ai * HALF + m * 16) * DM + col);
;             }
; #pragma unroll
;             for (int j = GB[grp]; j < GB[grp + 1]; ++j) {
;                 const int k = j >> 2, m = j & 3, ai = k >> 1, bj = k & 1, col = col0 + bj * HALF, kk = k - (GB[grp] >> 2);
;                 const u32x4 r = xv[j - GB[grp]];
;                 f32x4 x0 = {bflo(r.x), bfhi(r.x), bflo(r.y), bfhi(r.y)}, x1 = {bflo(r.z), bfhi(r.z), bflo(r.w), bfhi(r.w)};
;                 x0 = (x0 - st[m].x) * st[m].y * cl[kk][0] + cb[kk][0]; x1 = (x1 - st[m].x) * st[m].y * cl[kk][1] + cb[kk][1];
;                 const f32x4 o0 = x0 * ALPHA + cg[kk][0] * acc[ai][bj][m][0], o1 = x1 * ALPHA + cg[kk][1] * acc[ai][bj][m][1];
;                 u32x4 w; w.x = cvt_pk_bf16(o0[0], o0[1]); w.y = cvt_pk_bf16(o0[2], o0[3]); w.z = cvt_pk_bf16(o1[0], o1[1]); w.w = cvt_pk_bf16(o1[2], o1[3]);
;                 *(u32x4*)(z + (size_t)(row0 + ai * HALF + m * 16) * DM + col) = w;
;             }
	v_pk_fma_f32 v[116:117], v[116:117], v[204:205], v[122:123]
	v_pk_fma_f32 v[118:119], v[118:119], v[202:203], v[120:121]
	v_pk_mul_f32 v[120:121], v[126:127], s[22:23] op_sel_hi:[1,0]
	v_pk_mul_f32 v[122:123], v[124:125], s[22:23] op_sel_hi:[1,0]
	s_nop 0
	v_pk_fma_f32 v[122:123], v[114:115], v[198:199], v[122:123]
	v_pk_fma_f32 v[114:115], v[112:113], v[200:201], v[120:121]
	v_cvt_pk_bf16_f32 v112, v116, v117
	v_cvt_pk_bf16_f32 v113, v118, v119
	v_lshlrev_b32_e32 v118, 16, v150
	v_cvt_pk_bf16_f32 v114, v114, v115
	v_cvt_pk_bf16_f32 v115, v122, v123
	global_store_dwordx4 v[190:191], v[112:115], off
	v_and_b32_e32 v119, 0xffff0000, v150
	v_lshlrev_b32_e32 v116, 16, v151
	v_lshlrev_b32_e32 v114, 16, v148
	v_and_b32_e32 v115, 0xffff0000, v148
	v_lshlrev_b32_e32 v112, 16, v149
	v_and_b32_e32 v113, 0xffff0000, v149
	v_and_b32_e32 v117, 0xffff0000, v151
	v_sub_f32_e32 v113, v113, v178
	v_sub_f32_e32 v112, v112, v178
	v_sub_f32_e32 v115, v115, v178
	v_sub_f32_e32 v114, v114, v178
	v_pk_mul_f32 v[114:115], v[180:181], v[114:115] op_sel_hi:[0,1]
	v_pk_mul_f32 v[112:113], v[180:181], v[112:113] op_sel_hi:[0,1]
	v_sub_f32_e32 v117, v117, v178
	v_sub_f32_e32 v116, v116, v178
	v_sub_f32_e32 v119, v119, v178
	v_sub_f32_e32 v118, v118, v178
	v_pk_fma_f32 v[112:113], v[138:139], v[112:113], v[142:143]
	v_pk_fma_f32 v[114:115], v[136:137], v[114:115], v[140:141]
	v_pk_mul_f32 v[118:119], v[180:181], v[118:119] op_sel_hi:[0,1]
	v_pk_mul_f32 v[116:117], v[180:181], v[116:117] op_sel_hi:[0,1]
	v_pk_fma_f32 v[116:117], v[130:131], v[116:117], v[134:135]
	v_pk_fma_f32 v[118:119], v[128:129], v[118:119], v[132:133]
	v_pk_mul_f32 v[114:115], v[114:115], s[22:23] op_sel_hi:[1,0]
	v_pk_mul_f32 v[112:113], v[112:113], s[22:23] op_sel_hi:[1,0]
	v_pk_fma_f32 v[108:109], v[108:109], v[204:205], v[114:115]
	v_pk_fma_f32 v[110:111], v[110:111], v[202:203], v[112:113]
	v_pk_mul_f32 v[112:113], v[118:119], s[22:23] op_sel_hi:[1,0]
	v_pk_mul_f32 v[114:115], v[116:117], s[22:23] op_sel_hi:[1,0]
	s_nop 0
	v_pk_fma_f32 v[114:115], v[106:107], v[198:199], v[114:115]
	v_pk_fma_f32 v[106:107], v[104:105], v[200:201], v[112:113]
	v_cvt_pk_bf16_f32 v104, v108, v109
	v_cvt_pk_bf16_f32 v105, v110, v111
	v_lshlrev_b32_e32 v110, 16, v146
	v_cvt_pk_bf16_f32 v106, v106, v107
	v_cvt_pk_bf16_f32 v107, v114, v115
	global_store_dwordx4 v[188:189], v[104:107], off
	v_and_b32_e32 v111, 0xffff0000, v146
	v_lshlrev_b32_e32 v108, 16, v147
	v_lshlrev_b32_e32 v106, 16, v144
	v_and_b32_e32 v107, 0xffff0000, v144
	v_lshlrev_b32_e32 v104, 16, v145
	v_and_b32_e32 v105, 0xffff0000, v145
	v_and_b32_e32 v109, 0xffff0000, v147
	v_sub_f32_e32 v105, v105, v174
	v_sub_f32_e32 v104, v104, v174
	v_sub_f32_e32 v107, v107, v174
	v_sub_f32_e32 v106, v106, v174
	v_pk_mul_f32 v[106:107], v[176:177], v[106:107] op_sel_hi:[0,1]
	v_pk_mul_f32 v[104:105], v[176:177], v[104:105] op_sel_hi:[0,1]
	v_sub_f32_e32 v109, v109, v174
	v_sub_f32_e32 v108, v108, v174
	v_sub_f32_e32 v111, v111, v174
	v_sub_f32_e32 v110, v110, v174
	v_pk_fma_f32 v[104:105], v[138:139], v[104:105], v[142:143]
	v_pk_fma_f32 v[106:107], v[136:137], v[106:107], v[140:141]
	v_pk_mul_f32 v[110:111], v[176:177], v[110:111] op_sel_hi:[0,1]
	v_pk_mul_f32 v[108:109], v[176:177], v[108:109] op_sel_hi:[0,1]
	v_pk_fma_f32 v[108:109], v[130:131], v[108:109], v[134:135]
	v_pk_fma_f32 v[110:111], v[128:129], v[110:111], v[132:133]
	v_pk_mul_f32 v[106:107], v[106:107], s[22:23] op_sel_hi:[1,0]
	v_pk_mul_f32 v[104:105], v[104:105], s[22:23] op_sel_hi:[1,0]
	v_pk_fma_f32 v[100:101], v[100:101], v[204:205], v[106:107]
	v_pk_fma_f32 v[102:103], v[102:103], v[202:203], v[104:105]
	v_pk_mul_f32 v[104:105], v[110:111], s[22:23] op_sel_hi:[1,0]
	v_pk_mul_f32 v[106:107], v[108:109], s[22:23] op_sel_hi:[1,0]
	v_mov_b32_e32 v108, 0
	v_pk_fma_f32 v[106:107], v[98:99], v[198:199], v[106:107]
	v_pk_fma_f32 v[98:99], v[96:97], v[200:201], v[104:105]
	v_cvt_pk_bf16_f32 v96, v100, v101
	v_cvt_pk_bf16_f32 v97, v102, v103
	v_mov_b32_e32 v100, 0
	v_cvt_pk_bf16_f32 v98, v98, v99
	v_cvt_pk_bf16_f32 v99, v106, v107
	global_store_dwordx4 v[186:187], v[96:99], off
	global_load_dwordx4 v[112:115], v[168:169], off offset:512
	v_mov_b32_e32 v104, 1.0
	v_mov_b32_e32 v96, 1.0
	v_mov_b32_e32 v105, 1.0
	v_mov_b32_e32 v106, 1.0
	v_mov_b32_e32 v107, 1.0
	v_mov_b32_e32 v109, 0
	v_mov_b32_e32 v110, 0
	v_mov_b32_e32 v111, 0
	s_cbranch_vccnz .LBB0_202
	global_load_dwordx4 v[104:107], v[164:165], off offset:512
	global_load_dwordx4 v[108:111], v[166:167], off offset:512

; __device__ __forceinline__ unsigned cvt_pk_bf16(float lo, float hi) { unsigned r; asm volatile("v_cvt_pk_bf16_f32 %0, %1, %2" : "=v"(r) : "v"(lo), "v"(hi)); return r; }
; __device__ __forceinline__ float bflo(unsigned w) { return __uint_as_float(w << 16); }
; __device__ __forceinline__ float bfhi(unsigned w) { return __uint_as_float(w & 0xffff0000u); }
;     __device__ __forceinline__ void operator()(const f32x4 (&acc)[2][2][4][2], const Unit& u, int wr, int wc, int fr, int fq) const {
;     ...
;                 xv[j - GB[grp]] = *(const u32x4*)(z + (size_t)(row0 + ai * HALF + m * 16) * DM + col);
;             }
; #pragma unroll
;             for (int j = GB[grp]; j < GB[grp + 1]; ++j) {
;                 const int k = j >> 2, m = j & 3, ai = k >> 1, bj = k & 1, col = col0 + bj * HALF, kk = k - (GB[grp] >> 2);
;                 const u32x4 r = xv[j - GB[grp]];
;                 f32x4 x0 = {bflo(r.x), bfhi(r.x), bflo(r.y), bfhi(r.y)}, x1 = {bflo(r.z), bfhi(r.z), bflo(r.w), bfhi(r.w)};
;                 x0 = (x0 - st[m].x) * st[m].y * cl[kk][0] + cb[kk][0]; x1 = (x1 - st[m].x) * st[m].y * cl[kk][1] + cb[kk][1];
;                 const f32x4 o0 = x0 * ALPHA + cg[kk][0] * acc[ai][bj][m][0], o1 = x1 * ALPHA + cg[kk][1] * acc[ai][bj][m][1];
;                 u32x4 w; w.x = cvt_pk_bf16(o0[0], o0[1]); w.y = cvt_pk_bf16(o0[2], o0[3]); w.z = cvt_pk_bf16(o1[0], o1[1]); w.w = cvt_pk_bf16(o1[2], o1[3]);
;                 *(u32x4*)(z + (size_t)(row0 + ai * HALF + m * 16) * DM + col) = w;
;             }
.LBB0_204:
	s_waitcnt vmcnt(0)
	v_pk_add_f32 v[120:121], v[118:119], 1.0 op_sel_hi:[1,0]
	v_pk_add_f32 v[122:123], v[116:117], 1.0 op_sel_hi:[1,0]
	v_pk_add_f32 v[124:125], v[114:115], 1.0 op_sel_hi:[1,0]
	v_pk_add_f32 v[126:127], v[112:113], 1.0 op_sel_hi:[1,0]
	global_load_dwordx4 v[128:131], v[196:197], off offset:256
	global_load_dwordx4 v[132:135], v[190:191], off offset:256
	global_load_dwordx4 v[116:119], v[188:189], off offset:256
	global_load_dwordx4 v[112:115], v[186:187], off offset:256
	v_mov_b32_e32 v195, v194
	v_mov_b32_e32 v183, v182
	v_mov_b32_e32 v181, v180
	v_mov_b32_e32 v177, v176
	s_and_b64 vcc, exec, s[4:5]
	v_mov_b32_e32 v144, 0
	v_mov_b32_e32 v142, 1.0
	s_waitcnt vmcnt(0)
	v_lshlrev_b32_e32 v136, 16, v128
	v_and_b32_e32 v137, 0xffff0000, v128
	v_lshlrev_b32_e32 v128, 16, v129
	v_and_b32_e32 v129, 0xffff0000, v129
	v_lshlrev_b32_e32 v140, 16, v130
	v_and_b32_e32 v141, 0xffff0000, v130
	v_lshlrev_b32_e32 v138, 16, v131
	v_and_b32_e32 v139, 0xffff0000, v131
	v_sub_f32_e32 v129, v129, v192
	v_sub_f32_e32 v128, v128, v192
	v_sub_f32_e32 v131, v137, v192
	v_sub_f32_e32 v130, v136, v192
	v_mov_b32_e32 v136, v194
	v_mov_b32_e32 v137, v194
	v_pk_mul_f32 v[130:131], v[194:195], v[130:131]
	v_pk_mul_f32 v[128:129], v[136:137], v[128:129]
	v_sub_f32_e32 v139, v139, v192
	v_sub_f32_e32 v138, v138, v192
	v_sub_f32_e32 v141, v141, v192
	v_sub_f32_e32 v140, v140, v192
	v_pk_fma_f32 v[128:129], v[106:107], v[128:129], v[110:111]
	v_pk_fma_f32 v[130:131], v[104:105], v[130:131], v[108:109]
	v_pk_mul_f32 v[140:141], v[194:195], v[140:141]
	v_pk_mul_f32 v[136:137], v[136:137], v[138:139]
	v_pk_fma_f32 v[138:139], v[96:97], v[140:141], v[100:101]
	v_pk_fma_f32 v[136:137], v[98:99], v[136:137], v[102:103]
	v_pk_mul_f32 v[130:131], v[130:131], s[22:23] op_sel_hi:[1,0]
	v_pk_mul_f32 v[128:129], v[128:129], s[22:23] op_sel_hi:[1,0]
	v_pk_fma_f32 v[92:93], v[92:93], v[126:127], v[130:131]
	v_pk_fma_f32 v[94:95], v[94:95], v[124:125], v[128:129]
	v_pk_mul_f32 v[128:129], v[138:139], s[22:23] op_sel_hi:[1,0]
	v_pk_mul_f32 v[130:131], v[136:137], s[22:23] op_sel_hi:[1,0]
	v_mov_b32_e32 v136, 1.0
	v_pk_fma_f32 v[130:131], v[90:91], v[120:121], v[130:131]
	v_pk_fma_f32 v[90:91], v[88:89], v[122:123], v[128:129]
	v_cvt_pk_bf16_f32 v88, v92, v93
	v_cvt_pk_bf16_f32 v89, v94, v95
	v_lshlrev_b32_e32 v128, 16, v134
	v_cvt_pk_bf16_f32 v90, v90, v91
	v_cvt_pk_bf16_f32 v91, v130, v131
	global_store_dwordx4 v[196:197], v[88:91], off offset:256
	v_and_b32_e32 v129, 0xffff0000, v134
	v_lshlrev_b32_e32 v94, 16, v135
	v_lshlrev_b32_e32 v90, 16, v132
	v_and_b32_e32 v91, 0xffff0000, v132
	v_lshlrev_b32_e32 v88, 16, v133
	v_and_b32_e32 v89, 0xffff0000, v133
	v_and_b32_e32 v95, 0xffff0000, v135
	v_sub_f32_e32 v89, v89, v184
	v_sub_f32_e32 v88, v88, v184
	v_sub_f32_e32 v91, v91, v184
	v_sub_f32_e32 v90, v90, v184
	v_mov_b32_e32 v92, v182
	v_mov_b32_e32 v93, v182
	v_pk_mul_f32 v[90:91], v[182:183], v[90:91]
	v_pk_mul_f32 v[88:89], v[92:93], v[88:89]
	v_sub_f32_e32 v95, v95, v184
	v_sub_f32_e32 v94, v94, v184
	v_sub_f32_e32 v129, v129, v184
	v_sub_f32_e32 v128, v128, v184
	v_pk_fma_f32 v[88:89], v[106:107], v[88:89], v[110:111]
	v_pk_fma_f32 v[90:91], v[104:105], v[90:91], v[108:109]
	v_pk_mul_f32 v[128:129], v[182:183], v[128:129]
	v_pk_mul_f32 v[92:93], v[92:93], v[94:95]
	v_pk_fma_f32 v[94:95], v[96:97], v[128:129], v[100:101]
	v_pk_fma_f32 v[92:93], v[98:99], v[92:93], v[102:103]
	v_pk_mul_f32 v[90:91], v[90:91], s[22:23] op_sel_hi:[1,0]
	v_pk_mul_f32 v[88:89], v[88:89], s[22:23] op_sel_hi:[1,0]
	v_pk_fma_f32 v[84:85], v[84:85], v[126:127], v[90:91]
	v_pk_fma_f32 v[86:87], v[86:87], v[124:125], v[88:89]
	v_pk_mul_f32 v[88:89], v[94:95], s[22:23] op_sel_hi:[1,0]
	v_pk_mul_f32 v[90:91], v[92:93], s[22:23] op_sel_hi:[1,0]
	v_mov_b32_e32 v138, 0
	v_pk_fma_f32 v[90:91], v[82:83], v[120:121], v[90:91]
	v_pk_fma_f32 v[82:83], v[80:81], v[122:123], v[88:89]
	v_cvt_pk_bf16_f32 v80, v84, v85
	v_cvt_pk_bf16_f32 v81, v86, v87
	v_lshlrev_b32_e32 v88, 16, v118
	v_cvt_pk_bf16_f32 v82, v82, v83
	v_cvt_pk_bf16_f32 v83, v90, v91
	global_store_dwordx4 v[190:191], v[80:83], off offset:256
; __device__ __forceinline__ unsigned cvt_pk_bf16(float lo, float hi) { unsigned r; asm volatile("v_cvt_pk_bf16_f32 %0, %1, %2" : "=v"(r) : "v"(lo), "v"(hi)); return r; }
; __device__ __forceinline__ float bflo(unsigned w) { return __uint_as_float(w << 16); }
; __device__ __forceinline__ float bfhi(unsigned w) { return __uint_as_float(w & 0xffff0000u); }
;     __device__ __forceinline__ void operator()(const f32x4 (&acc)[2][2][4][2], const Unit& u, int wr, int wc, int fr, int fq) const {
;     ...
;             if (grp == 0 || grp == 2) {
; #pragma unroll
;                 for (int m = 0; m < 4; ++m) st[m] = ln ? *(const f32x2*)(stats + 2 * (row0 + (grp ? HALF : 0) + m * 16)) : (f32x2){0.f, 1.f};
;             }
; #pragma unroll
;             for (int j = GB[grp]; j < GB[grp + 1]; ++j) {
;                 const int k = j >> 2, m = j & 3, ai = k >> 1, col = col0 + (k & 1) * HALF, kk = k - (GB[grp] >> 2);
;                 if (m == 0) {
; #pragma unroll
;                     for (int n = 0; n < 2; ++n) { cg[kk][n] = *(const f32x4*)(gb + col + 4 * n) + 1.0f; cl[kk][n] = (f32x4){1.f, 1.f, 1.f, 1.f}; cb[kk][n] = (f32x4){0.f, 0.f, 0.f, 0.f};
;                         if (ln) { cl[kk][n] = *(const f32x4*)(lng + col + 4 * n); cb[kk][n] = *(const f32x4*)(lnb + col + 4 * n); } }
;                 }
;                 xv[j - GB[grp]] = *(const u32x4*)(z + (size_t)(row0 + ai * HALF + m * 16) * DM + col);
;             }
; #pragma unroll
;             for (int j = GB[grp]; j < GB[grp + 1]; ++j) {
;                 const int k = j >> 2, m = j & 3, ai = k >> 1, bj = k & 1, col = col0 + bj * HALF, kk = k - (GB[grp] >> 2);
;                 const u32x4 r = xv[j - GB[grp]];
;                 f32x4 x0 = {bflo(r.x), bfhi(r.x), bflo(r.y), bfhi(r.y)}, x1 = {bflo(r.z), bfhi(r.z), bflo(r.w), bfhi(r.w)};
;                 x0 = (x0 - st[m].x) * st[m].y * cl[kk][0] + cb[kk][0]; x1 = (x1 - st[m].x) * st[m].y * cl[kk][1] + cb[kk][1];
;                 const f32x4 o0 = x0 * ALPHA + cg[kk][0] * acc[ai][bj][m][0], o1 = x1 * ALPHA + cg[kk][1] * acc[ai][bj][m][1];
;                 u32x4 w; w.x = cvt_pk_bf16(o0[0], o0[1]); w.y = cvt_pk_bf16(o0[2], o0[3]); w.z = cvt_pk_bf16(o1[0], o1[1]); w.w = cvt_pk_bf16(o1[2], o1[3]);
;                 *(u32x4*)(z + (size_t)(row0 + ai * HALF + m * 16) * DM + col) = w;
;             }
	v_and_b32_e32 v89, 0xffff0000, v118
	v_lshlrev_b32_e32 v86, 16, v119
	v_lshlrev_b32_e32 v82, 16, v116
	v_and_b32_e32 v83, 0xffff0000, v116
	v_lshlrev_b32_e32 v80, 16, v117
	v_and_b32_e32 v81, 0xffff0000, v117
	v_and_b32_e32 v87, 0xffff0000, v119
	v_sub_f32_e32 v81, v81, v178
	v_sub_f32_e32 v80, v80, v178
	v_sub_f32_e32 v83, v83, v178
	v_sub_f32_e32 v82, v82, v178
	v_mov_b32_e32 v84, v180
	v_mov_b32_e32 v85, v180
	v_pk_mul_f32 v[82:83], v[180:181], v[82:83]
	v_pk_mul_f32 v[80:81], v[84:85], v[80:81]
	v_sub_f32_e32 v87, v87, v178
	v_sub_f32_e32 v86, v86, v178
	v_sub_f32_e32 v89, v89, v178
	v_sub_f32_e32 v88, v88, v178
	v_pk_fma_f32 v[80:81], v[106:107], v[80:81], v[110:111]
	v_pk_fma_f32 v[82:83], v[104:105], v[82:83], v[108:109]
	v_pk_mul_f32 v[88:89], v[180:181], v[88:89]
	v_pk_mul_f32 v[84:85], v[84:85], v[86:87]
	v_pk_fma_f32 v[86:87], v[96:97], v[88:89], v[100:101]
	v_pk_fma_f32 v[84:85], v[98:99], v[84:85], v[102:103]
	v_pk_mul_f32 v[82:83], v[82:83], s[22:23] op_sel_hi:[1,0]
	v_pk_mul_f32 v[80:81], v[80:81], s[22:23] op_sel_hi:[1,0]
	v_pk_fma_f32 v[76:77], v[76:77], v[126:127], v[82:83]
	v_pk_fma_f32 v[78:79], v[78:79], v[124:125], v[80:81]
	v_pk_mul_f32 v[80:81], v[86:87], s[22:23] op_sel_hi:[1,0]
	v_pk_mul_f32 v[82:83], v[84:85], s[22:23] op_sel_hi:[1,0]
	s_nop 0
	v_pk_fma_f32 v[82:83], v[74:75], v[120:121], v[82:83]
	v_pk_fma_f32 v[74:75], v[72:73], v[122:123], v[80:81]
	v_cvt_pk_bf16_f32 v72, v76, v77
	v_cvt_pk_bf16_f32 v73, v78, v79
	v_lshlrev_b32_e32 v80, 16, v114
	v_cvt_pk_bf16_f32 v74, v74, v75
	v_cvt_pk_bf16_f32 v75, v82, v83
	global_store_dwordx4 v[188:189], v[72:75], off offset:256
	v_and_b32_e32 v81, 0xffff0000, v114
	v_lshlrev_b32_e32 v78, 16, v115
	v_lshlrev_b32_e32 v74, 16, v112
	v_and_b32_e32 v75, 0xffff0000, v112
	v_lshlrev_b32_e32 v72, 16, v113
	v_and_b32_e32 v73, 0xffff0000, v113
	v_and_b32_e32 v79, 0xffff0000, v115
	v_sub_f32_e32 v73, v73, v174
	v_sub_f32_e32 v72, v72, v174
	v_sub_f32_e32 v75, v75, v174
	v_sub_f32_e32 v74, v74, v174
	v_mov_b32_e32 v76, v176
	v_mov_b32_e32 v77, v176
	v_pk_mul_f32 v[74:75], v[176:177], v[74:75]
	v_pk_mul_f32 v[72:73], v[76:77], v[72:73]
	v_sub_f32_e32 v79, v79, v174
	v_sub_f32_e32 v78, v78, v174
	v_sub_f32_e32 v81, v81, v174
	v_sub_f32_e32 v80, v80, v174
	v_pk_fma_f32 v[72:73], v[106:107], v[72:73], v[110:111]
	v_pk_fma_f32 v[74:75], v[104:105], v[74:75], v[108:109]
	v_pk_mul_f32 v[80:81], v[176:177], v[80:81]
	v_pk_mul_f32 v[76:77], v[76:77], v[78:79]
	v_pk_fma_f32 v[78:79], v[96:97], v[80:81], v[100:101]
	v_pk_fma_f32 v[76:77], v[98:99], v[76:77], v[102:103]
	v_pk_mul_f32 v[74:75], v[74:75], s[22:23] op_sel_hi:[1,0]
	v_pk_mul_f32 v[72:73], v[72:73], s[22:23] op_sel_hi:[1,0]
	v_pk_fma_f32 v[68:69], v[68:69], v[126:127], v[74:75]
	v_pk_fma_f32 v[70:71], v[70:71], v[124:125], v[72:73]
	v_pk_mul_f32 v[72:73], v[78:79], s[22:23] op_sel_hi:[1,0]
	v_pk_mul_f32 v[74:75], v[76:77], s[22:23] op_sel_hi:[1,0]
	s_nop 0
	v_pk_fma_f32 v[74:75], v[66:67], v[120:121], v[74:75]
	v_pk_fma_f32 v[66:67], v[64:65], v[122:123], v[72:73]
	v_cvt_pk_bf16_f32 v64, v68, v69
	v_cvt_pk_bf16_f32 v65, v70, v71
	s_nop 0
	v_cvt_pk_bf16_f32 v66, v66, v67
	v_cvt_pk_bf16_f32 v67, v74, v75
	global_store_dwordx4 v[186:187], v[64:67], off offset:256
	v_mov_b32_e32 v128, 1.0
	v_mov_b32_e32 v130, 0
	v_mov_b32_e32 v134, 0
	v_mov_b32_e32 v132, 1.0
	s_cbranch_vccnz .Lres_st2_skip
	v_lshl_add_u64 v[64:65], v[170:171], 2, s[14:15]
	global_load_dwordx2 v[144:145], v[64:65], off offset:1024
	global_load_dwordx2 v[138:139], v[64:65], off offset:1152
	global_load_dwordx2 v[134:135], v[64:65], off offset:1280
	global_load_dwordx2 v[130:131], v[64:65], off offset:1408
.Lres_st2_skip:
.LBB0_212:
	global_load_dwordx4 v[80:83], v[168:169], off
	v_mov_b32_e32 v88, 0
	v_mov_b32_e32 v84, 1.0
	s_and_b64 vcc, exec, s[4:5]
	v_mov_b32_e32 v92, 1.0
	v_mov_b32_e32 v93, 1.0
	v_mov_b32_e32 v94, 1.0
	v_mov_b32_e32 v95, 1.0
	v_mov_b32_e32 v96, 0
	v_mov_b32_e32 v97, 0
	v_mov_b32_e32 v98, 0
	v_mov_b32_e32 v99, 0
	s_cbranch_vccnz .LBB0_214
	global_load_dwordx4 v[92:95], v[164:165], off
	global_load_dwordx4 v[96:99], v[166:167], off
